# v6 + phase-1 norm rows: x and pos-embedding loads of both rows issued together (16 in flight) instead of a vmcnt(0) after each pos-embedding load
# speedup vs baseline: 1.0094x; 1.0056x over previous
.LBB0_134:
	s_or_b64 exec, exec, s[28:29]
	v_lshlrev_b32_e32 v2, 5, v4
	v_and_b32_e32 v52, 63, v37
	v_and_b32_e32 v32, 0xf800, v2
	v_lshl_add_u64 v[2:3], s[20:21], 0, v[32:33]
	v_lshlrev_b32_e32 v32, 4, v52
	v_lshl_add_u64 v[0:1], v[0:1], 0, v[32:33]
	global_load_dwordx4 v[24:27], v[0:1], off
	v_lshlrev_b32_e32 v36, 2, v52
	v_lshlrev_b32_e32 v32, 2, v36
	s_and_saveexec_b64 s[28:29], s[4:5]
	s_cbranch_execz .LBB0_136
	v_lshl_add_u64 v[6:7], v[2:3], 0, v[32:33]
	global_load_dwordx4 v[132:135], v[6:7], off
.LBB0_136:
	s_or_b64 exec, exec, s[28:29]
	global_load_dwordx4 v[16:19], v[0:1], off offset:1024
	s_and_saveexec_b64 s[28:29], s[4:5]
	s_cbranch_execz .LBB0_138
	v_lshl_add_u64 v[2:3], v[2:3], 0, v[32:33]
	global_load_dwordx4 v[136:139], v[2:3], off offset:1024
.LBB0_138:
	s_or_b64 exec, exec, s[28:29]
	global_load_dwordx4 v[8:11], v[0:1], off offset:2048
	v_lshlrev_b32_e32 v2, 11, v4
	v_and_b32_e32 v2, 0x1f000, v2
	v_mov_b32_e32 v3, v33
	v_lshl_add_u64 v[4:5], s[16:17], 0, v[2:3]
	s_and_saveexec_b64 s[28:29], s[4:5]
	s_cbranch_execz .LBB0_140
	v_lshl_add_u64 v[2:3], v[4:5], 0, v[32:33]
	v_add_co_u32_e32 v2, vcc, 0xe8fa000, v2
	s_nop 1
	v_addc_co_u32_e32 v3, vcc, 0, v3, vcc
	global_load_dwordx4 v[140:143], v[2:3], off
.LBB0_140:
	s_or_b64 exec, exec, s[28:29]
	global_load_dwordx4 v[0:3], v[0:1], off offset:3072
	s_and_saveexec_b64 s[28:29], s[4:5]
	s_cbranch_execz .LBB0_142
	v_lshl_add_u64 v[4:5], v[4:5], 0, v[32:33]
	v_add_co_u32_e32 v4, vcc, 0xe8fa000, v4
	s_nop 1
	v_addc_co_u32_e32 v5, vcc, 0, v5, vcc
	global_load_dwordx4 v[144:147], v[4:5], off offset:1024
.LBB0_142:
	s_or_b64 exec, exec, s[28:29]
	v_add_u32_e32 v42, 1, v34
	v_ashrrev_i32_e32 v43, 31, v42
	s_and_saveexec_b64 s[28:29], s[6:7]
	s_xor_b64 s[6:7], exec, s[28:29]
	s_cbranch_execz .LBB0_144
	v_lshlrev_b64 v[4:5], 12, v[42:43]
	s_waitcnt lgkmcnt(0)
	v_lshl_add_u64 v[4:5], s[12:13], 0, v[4:5]

.LBB0_146:
	s_or_b64 exec, exec, s[6:7]
	v_lshl_add_u64 v[4:5], v[4:5], 0, v[32:33]
	global_load_dwordx4 v[28:31], v[4:5], off
	v_lshlrev_b32_e32 v6, 5, v39
	v_and_b32_e32 v6, 0xf800, v6
	v_mov_b32_e32 v7, v33
	v_lshl_add_u64 v[6:7], s[20:21], 0, v[6:7]
	s_and_saveexec_b64 s[6:7], s[4:5]
	s_cbranch_execz .LBB0_148
	v_lshl_add_u64 v[12:13], v[6:7], 0, v[32:33]
	global_load_dwordx4 v[148:151], v[12:13], off
.LBB0_148:
	s_or_b64 exec, exec, s[6:7]
	global_load_dwordx4 v[20:23], v[4:5], off offset:1024
	s_and_saveexec_b64 s[6:7], s[4:5]
	s_cbranch_execz .LBB0_150
	v_lshl_add_u64 v[6:7], v[6:7], 0, v[32:33]
	global_load_dwordx4 v[152:155], v[6:7], off offset:1024
.LBB0_150:
	s_or_b64 exec, exec, s[6:7]
	global_load_dwordx4 v[12:15], v[4:5], off offset:2048
	v_lshlrev_b32_e32 v6, 11, v39
	v_and_b32_e32 v6, 0x1f800, v6
	v_mov_b32_e32 v7, v33
	v_lshl_add_u64 v[40:41], s[16:17], 0, v[6:7]
	s_and_saveexec_b64 s[6:7], s[4:5]
	s_cbranch_execz .LBB0_152
	v_lshl_add_u64 v[6:7], v[40:41], 0, v[32:33]
	v_add_co_u32_e32 v6, vcc, 0xe8fa000, v6
	s_nop 1
	v_addc_co_u32_e32 v7, vcc, 0, v7, vcc
	global_load_dwordx4 v[156:159], v[6:7], off
.LBB0_152:
	s_or_b64 exec, exec, s[6:7]
	global_load_dwordx4 v[4:7], v[4:5], off offset:3072
	s_and_saveexec_b64 s[6:7], s[4:5]
	s_cbranch_execz .LBB0_154
	v_lshl_add_u64 v[40:41], v[40:41], 0, v[32:33]
	v_add_co_u32_e32 v40, vcc, 0xe8fa000, v40
	s_nop 1
	v_addc_co_u32_e32 v41, vcc, 0, v41, vcc
	global_load_dwordx4 v[168:171], v[40:41], off offset:1024
.LBB0_154:
	s_or_b64 exec, exec, s[6:7]
	s_and_saveexec_b64 s[28:29], s[4:5]
	s_cbranch_execz .Lp1_r0_ctx
	s_waitcnt vmcnt(8)
	v_pk_add_f32 v[26:27], v[26:27], v[134:135]
	v_pk_add_f32 v[24:25], v[24:25], v[132:133]
	v_pk_add_f32 v[18:19], v[18:19], v[138:139]
	v_pk_add_f32 v[16:17], v[16:17], v[136:137]
	v_pk_add_f32 v[10:11], v[10:11], v[142:143]
	v_pk_add_f32 v[8:9], v[8:9], v[140:141]
	v_pk_add_f32 v[2:3], v[2:3], v[146:147]
	v_pk_add_f32 v[0:1], v[0:1], v[144:145]
	s_or_b64 exec, exec, s[28:29]
	s_branch .Lp1_r0_join
.Lp1_r0_ctx:
	s_or_b64 exec, exec, s[28:29]
	s_waitcnt vmcnt(4)
.Lp1_r0_join:
	v_mul_f32_e32 v166, v25, v25
	v_mul_f32_e32 v167, v17, v17
	v_fmac_f32_e32 v166, v24, v24
	v_fmac_f32_e32 v167, v16, v16
	v_fmac_f32_e32 v166, v26, v26
	v_fmac_f32_e32 v167, v18, v18
	v_fmac_f32_e32 v166, v27, v27
	v_fmac_f32_e32 v167, v19, v19
	v_add_f32_e32 v166, v166, v167
	v_mul_f32_e32 v167, v9, v9
	v_fmac_f32_e32 v167, v8, v8
	v_fmac_f32_e32 v167, v10, v10
	v_fmac_f32_e32 v167, v11, v11
	v_add_f32_e32 v166, v166, v167
	v_mul_f32_e32 v167, v1, v1
	v_fmac_f32_e32 v167, v0, v0
	v_fmac_f32_e32 v167, v2, v2
	v_fmac_f32_e32 v167, v3, v3
	v_add_f32_e32 v166, v166, v167
	s_nop 1
	v_add_f32_dpp v166, v166, v166 quad_perm:[1,0,3,2] row_mask:0xf bank_mask:0xf bound_ctrl:1
	s_nop 1
	v_add_f32_dpp v166, v166, v166 quad_perm:[2,3,0,1] row_mask:0xf bank_mask:0xf bound_ctrl:1
	s_nop 1
	v_add_f32_dpp v166, v166, v166 row_half_mirror row_mask:0xf bank_mask:0xf bound_ctrl:1
	s_nop 1
	v_add_f32_dpp v166, v166, v166 row_ror:8 row_mask:0xf bank_mask:0xf bound_ctrl:1
	v_mov_b32_e32 v167, v166
	s_nop 1
	v_permlane16_swap_b32_e32 v166, v167
	v_add_f32_e32 v44, v166, v167
	v_mov_b32_e32 v45, v44
	s_nop 1
	v_permlane32_swap_b32_e32 v44, v45
	s_and_saveexec_b64 s[6:7], s[4:5]
	s_cbranch_execz .Lp1_r1_ctx
	s_waitcnt vmcnt(0)
	v_pk_add_f32 v[30:31], v[30:31], v[150:151]
	v_pk_add_f32 v[28:29], v[28:29], v[148:149]
	v_pk_add_f32 v[22:23], v[22:23], v[154:155]
	v_pk_add_f32 v[20:21], v[20:21], v[152:153]
	v_pk_add_f32 v[14:15], v[14:15], v[158:159]
	v_pk_add_f32 v[12:13], v[12:13], v[156:157]
	v_pk_add_f32 v[6:7], v[6:7], v[170:171]
	v_pk_add_f32 v[4:5], v[4:5], v[168:169]
